# next-block prefetch: the window epilogue of query block kk issues the first two compressed K/V stages and the Q fragments of query block kk+1
# speedup vs baseline: 1.0038x; 1.0038x over previous
; #define LAS __attribute__((address_space(3)))
; __device__ __forceinline__ void nsa_quad_pre(int bg, int quad, const bf16_t* Q, const bf16_t* KV, const bf16_t* KCMP, const bf16_t* VCMPT, const float* GN, bf16_t* ONSA, ...
;     const int r16 = lane & 15, q4 = lane >> 4, b = bg >> 2, g = bg & 3, t0 = quad * 4;
;     const unsigned koff = (unsigned)(r16 * 64 + q4 * 8) * 2u, voffS = (unsigned)(r16 * SEQ + q4 * 8) * 2u, voffC = (unsigned)(r16 * 512 + q4 * 8) * 2u;
;     const char* KWb = (const char*)(KV + 4 * (size_t)MTOK * 256 + (size_t)bg * SEQ * 64); const char* VWb = (const char*)(KV + 5 * (size_t)MTOK * 256 + (size_t)bg * 64 * SEQ);
;     const char* KCb = (const char*)(KCMP + (size_t)bg * 512 * 64); const char* VCb = (const char*)(VCMPT + (size_t)bg * 64 * 512);
;     ...
;     const size_t qoff = (size_t)(b * SEQ + t0 + (r16 & 3)) * 1024 + (g * 4 + (r16 >> 2)) * 64 + q4 * 8;
;     { const bf16x8 a0 = *(const bf16x8*)(Q + qoff), a1 = *(const bf16x8*)(Q + qoff + 32); *(LAS bf16x8*)(qfw + lane * 8) = a0; *(LAS bf16x8*)(qfw + 512 + lane * 8) = a1; }
;     const LAS bf16_t* qf = qfw + lane * 8;
;     const LAS float* bt = btab + q4 * 1028;
;     const f32x4 z4 = {0.f, 0.f, 0.f, 0.f};
;     KFrag KF; VFrag VF; f32x4 sc[4];
;     const int w_lo = (t0 - 511 > 0 ? t0 - 511 : 0) >> 6, w_hi = t0 >> 6;
;     f32x4 oc[4] = {z4, z4, z4, z4};
;     const int tl = t0 + 3, nvmax = tl >= 31 ? ((tl - 31) >> 4) + 1 : 0, ngr = (nvmax + 63) >> 6;
;     if (ngr > 0) {
;         float ls[4] = {0.f, 0.f, 0.f, 0.f};
;         load_k(KF, KP_C(0));
; __device__ __forceinline__ void nsa_phase(LAS unsigned char* lds, const bf16_t* Q, const bf16_t* KV, const bf16_t* KCMP, const bf16_t* VCMPT, const float* GN, const float* rel_bias, bf16_t* ONSA,
;                                           int tid, int lane, int wave) {
;     ...
;                 const int qb = (kk & 1) ? (32 * kk + 31 - idx) : (32 * kk + idx);
;                 nsa_quad_pre(bg, qb * 16 + wave * 2, Q, KV, KCMP, VCMPT, GN, ONSA, btab, Pb, psum, selall + (wave * 2) * 64, qfw, lane);
.LBB0_738:
	s_lshl_b32 s1, s3, 5
	s_sub_i32 s14, s1, s91
	s_and_b32 s0, s3, 1
	s_add_i32 s14, s14, 31
	s_add_i32 s1, s1, s91
	s_cmp_eq_u32 s0, 0
	s_cselect_b32 s18, s1, s14
	v_and_b32_e32 v232, 15, v184
	v_lshrrev_b32_e32 v233, 4, v184
	v_and_b32_e32 v234, 3, v232
	v_lshrrev_b32_e32 v235, 2, v232
	v_mul_u32_u24_e32 v173, 0x1010, v235
	ds_read_b32 v225, v173 offset:4096
	v_mov_b32_e32 v252, 0xf149f2ca
	v_and_b32_e32 v253, 1, v235
	v_xor_b32_e32 v0, v233, v234
	v_lshlrev_b32_e32 v0, 4, v0
	v_lshl_add_u32 v0, v253, 6, v0
	v_lshl_add_u32 v98, v235, 3, v234
	v_lshl_add_u32 v176, v98, 7, v0
	s_lshl_b32 s33, s80, 7
	v_lshl_add_u32 v177, v232, 7, v0
	v_subrev_u32_e32 v177, s33, v177
	v_lshlrev_b32_e32 v98, 7, v253
	v_sub_u32_e32 v178, 64, v98
	v_lshrrev_b32_e32 v98, 3, v184
	v_and_b32_e32 v99, 7, v184
	s_lshr_b32 s0, s80, 3
	s_and_b32 s1, s0, 1
	s_lshl_b32 s1, s1, 2
	v_and_b32_e32 v253, 3, v98
	v_or_b32_e32 v253, s1, v253
	v_xor_b32_e32 v253, v99, v253
	v_add_u32_e32 v0, s80, v98
	v_lshlrev_b32_e32 v174, 7, v0
	v_lshl_add_u32 v174, v253, 4, v174
	v_xor_b32_e32 v253, v99, v98
	v_lshlrev_b32_e32 v175, 10, v0
	v_lshl_add_u32 v175, v253, 4, v175
	s_add_i32 s94, s33, 0xa040
	s_add_i32 s95, s33, 0x1dc40
	s_add_i32 s46, s33, 0x20200
	s_lshr_b32 s15, s97, 13
	s_lshl_b32 s15, s15, 2
	s_and_b32 s1, s88, 3
	s_or_b32 s15, s15, s1
	s_lshl_b32 s15, s15, 16
	s_add_u32 s68, s30, 0x38110000
	s_addc_u32 s69, s31, 0
	s_add_u32 s68, s68, s15
	s_addc_u32 s69, s69, 0
	s_add_u32 s70, s30, 0x38210000
	s_addc_u32 s71, s31, 0
	s_add_u32 s70, s70, s15
	s_addc_u32 s71, s71, 0
	s_lshl_b32 s74, s18, 2
	s_add_i32 s74, s74, 66
	s_lshr_b32 s74, s74, 6
	s_mov_b32 s75, 0
	v_lshlrev_b32_e32 v98, 7, v233
	v_sub_u32_e32 v172, v234, v98
	v_add_u32_e32 v172, 0xffffffe1, v172
	s_lshl_b32 s0, s80, 10
	s_add_i32 s0, s0, 56384
	v_lshlrev_b32_e32 v215, 11, v234
	v_lshl_add_u32 v215, v233, 5, v215
	v_add_u32_e32 v215, s0, v215
	s_cmp_lg_u32 s3, 0
	s_cbranch_scc1 .Lhdr_prefetched
	s_mov_b32 s92, 0
	s_mov_b32 s93, 0
	s_lshl_b32 s0, s92, 13
	s_add_i32 s0, s0, s33
	s_add_i32 m0, s0, 16448
	s_lshl_b32 s1, s93, 13
	s_add_u32 s72, s68, s1
	s_addc_u32 s73, s69, 0
	global_load_lds_dwordx4 v174, s[72:73]
	s_cmp_eq_u32 s92, 1
	s_cselect_b32 s0, s95, s94
	s_cmp_eq_u32 s92, 2
	s_cselect_b32 m0, s46, s0
	s_lshl_b32 s1, s93, 7
	s_add_u32 s72, s70, s1
	s_addc_u32 s73, s71, 0
	global_load_lds_dwordx4 v175, s[72:73]
	s_add_i32 s93, s93, 1
	s_cmp_ge_i32 s93, s74
	s_cselect_b32 s93, 0, s93
	s_add_i32 s92, s92, 1
	s_cmp_eq_u32 s92, 3
	s_cselect_b32 s92, 0, s92
	s_lshl_b32 s0, s92, 13
	s_add_i32 s0, s0, s33
	s_add_i32 m0, s0, 16448
	s_lshl_b32 s1, s93, 13
	s_add_u32 s72, s68, s1
	s_addc_u32 s73, s69, 0
	global_load_lds_dwordx4 v174, s[72:73]
	s_cmp_eq_u32 s92, 1
	s_cselect_b32 s0, s95, s94
	s_cmp_eq_u32 s92, 2
	s_cselect_b32 m0, s46, s0
	s_lshl_b32 s1, s93, 7
	s_add_u32 s72, s70, s1
	s_addc_u32 s73, s71, 0
	global_load_lds_dwordx4 v175, s[72:73]
	s_add_i32 s93, s93, 1
	s_cmp_ge_i32 s93, s74
	s_cselect_b32 s93, 0, s93
	s_add_i32 s92, s92, 1
	s_cmp_eq_u32 s92, 3
	s_cselect_b32 s92, 0, s92
	s_lshl_b32 s0, s18, 6
	s_add_i32 s0, s0, s97
	s_add_i32 s0, s0, s80
	v_add_u32_e32 v253, s0, v234
	s_and_b32 s1, s88, 3
	s_lshl_b32 s1, s1, 2
	v_add_u32_e32 v98, s1, v235
	v_lshlrev_b32_e32 v98, 7, v98
	v_lshl_add_u32 v98, v253, 11, v98
	v_lshl_add_u32 v98, v233, 4, v98
	v_add_u32_e32 v99, 0x2000, v98
	s_add_u32 s72, s30, 0x29900000
	s_addc_u32 s73, s31, 0
	global_load_dwordx4 v[34:37], v98, s[72:73] offset:0
	global_load_dwordx4 v[38:41], v98, s[72:73] offset:64
	global_load_dwordx4 v[42:45], v99, s[72:73] offset:0
	global_load_dwordx4 v[46:49], v99, s[72:73] offset:64
	s_branch .Lhdr_join
.Lhdr_prefetched:
	s_mov_b32 s92, 2
	s_cmp_gt_u32 s74, 2
	s_cselect_b32 s93, 2, 0
.Lhdr_join:
	s_waitcnt lgkmcnt(0)
	s_lshl_b32 s47, s18, 6
	s_add_i32 s47, s47, s80
	v_and_b32_e32 v232, 15, v184
	v_and_b32_e32 v234, 3, v232
	v_lshrrev_b32_e32 v235, 2, v232
	s_add_i32 s0, s47, s97
	v_add_u32_e32 v253, s0, v234
	s_and_b32 s1, s88, 3
	s_lshl_b32 s1, s1, 2
	v_add_u32_e32 v0, s1, v235
	v_mul_u32_u24_e32 v99, 0xc0, v253
	v_mul_u32_u24_e32 v0, 12, v0
	v_add_u32_e32 v99, v99, v0
	s_add_u32 s72, s30, 0x38310000
	s_addc_u32 s73, s31, 0
	global_load_dword v227, v99, s[72:73]
	v_mov_b32_e32 v2, 0
	v_mov_b32_e32 v3, 0
	v_mov_b32_e32 v4, 0
	v_mov_b32_e32 v5, 0
	v_mov_b32_e32 v6, 0
	v_mov_b32_e32 v7, 0
	v_mov_b32_e32 v8, 0
	v_mov_b32_e32 v9, 0
	v_mov_b32_e32 v10, 0
	v_mov_b32_e32 v11, 0
	v_mov_b32_e32 v12, 0
	v_mov_b32_e32 v13, 0
	v_mov_b32_e32 v14, 0
	v_mov_b32_e32 v15, 0
	v_mov_b32_e32 v16, 0
	v_mov_b32_e32 v17, 0
	s_sub_i32 s0, s47, 28
	s_ashr_i32 s0, s0, 4
	s_add_i32 s0, s0, 64
	s_ashr_i32 s53, s0, 6
	s_cmp_gt_i32 s47, 27
	s_cselect_b32 s53, s53, 0
	s_sub_i32 s0, s47, 2063
	s_ashr_i32 s52, s0, 10
	s_add_i32 s52, s52, 1
	s_max_i32 s52, s52, 0
	s_min_i32 s52, s52, s53
	v_add_u32_e32 v99, s47, v172
	v_and_b32_e32 v98, 15, v184
	v_mov_b32_e32 v170, 0
	s_waitcnt vmcnt(0)
	s_barrier
	s_mov_b32 s57, 0

; #define LAS __attribute__((address_space(3)))
; __device__ __forceinline__ void nsa_quad_pre(int bg, int quad, const bf16_t* Q, const bf16_t* KV, const bf16_t* KCMP, const bf16_t* VCMPT, const float* GN, bf16_t* ONSA, ...
;     const int r16 = lane & 15, q4 = lane >> 4, b = bg >> 2, g = bg & 3, t0 = quad * 4;
;     const unsigned koff = (unsigned)(r16 * 64 + q4 * 8) * 2u, voffS = (unsigned)(r16 * SEQ + q4 * 8) * 2u, voffC = (unsigned)(r16 * 512 + q4 * 8) * 2u;
;     const char* KWb = (const char*)(KV + 4 * (size_t)MTOK * 256 + (size_t)bg * SEQ * 64); const char* VWb = (const char*)(KV + 5 * (size_t)MTOK * 256 + (size_t)bg * 64 * SEQ);
;     const char* KCb = (const char*)(KCMP + (size_t)bg * 512 * 64); const char* VCb = (const char*)(VCMPT + (size_t)bg * 64 * 512);
;     ...
;     const size_t qoff = (size_t)(b * SEQ + t0 + (r16 & 3)) * 1024 + (g * 4 + (r16 >> 2)) * 64 + q4 * 8;
;     { const bf16x8 a0 = *(const bf16x8*)(Q + qoff), a1 = *(const bf16x8*)(Q + qoff + 32); *(LAS bf16x8*)(qfw + lane * 8) = a0; *(LAS bf16x8*)(qfw + 512 + lane * 8) = a1; }
;     const LAS bf16_t* qf = qfw + lane * 8;
;     const LAS float* bt = btab + q4 * 1028;
;     const f32x4 z4 = {0.f, 0.f, 0.f, 0.f};
;     KFrag KF; VFrag VF; f32x4 sc[4];
;     const int w_lo = (t0 - 511 > 0 ? t0 - 511 : 0) >> 6, w_hi = t0 >> 6;
;     f32x4 oc[4] = {z4, z4, z4, z4};
;     const int tl = t0 + 3, nvmax = tl >= 31 ? ((tl - 31) >> 4) + 1 : 0, ngr = (nvmax + 63) >> 6;
;     if (ngr > 0) {
;         float ls[4] = {0.f, 0.f, 0.f, 0.f};
;         load_k(KF, KP_C(0));
; __device__ __forceinline__ void nsa_phase(LAS unsigned char* lds, const bf16_t* Q, const bf16_t* KV, const bf16_t* KCMP, const bf16_t* VCMPT, const float* GN, const float* rel_bias, bf16_t* ONSA,
;                                           int tid, int lane, int wave) {
;     ...
;                 const int qb = (kk & 1) ? (32 * kk + 31 - idx) : (32 * kk + idx);
.Lnsa_noearly_29:
.Lnsa_blk_done:
	s_nop 7
	s_nop 7
	s_cmp_lg_u32 s54, 1
	s_cbranch_scc1 .Lepi_nopref
	s_cmp_gt_u32 s3, 2
	s_cbranch_scc1 .Lepi_nopref
	s_add_i32 s0, s3, 1
	s_lshl_b32 s1, s0, 5
	s_sub_i32 s14, s1, s91
	s_and_b32 s0, s0, 1
	s_add_i32 s14, s14, 31
	s_add_i32 s1, s1, s91
	s_cmp_eq_u32 s0, 0
	s_cselect_b32 s34, s1, s14
	v_and_b32_e32 v232, 15, v184
	v_lshrrev_b32_e32 v233, 4, v184
	v_and_b32_e32 v234, 3, v232
	v_lshrrev_b32_e32 v235, 2, v232
	v_and_b32_e32 v253, 1, v235
	v_xor_b32_e32 v0, v233, v234
	v_lshlrev_b32_e32 v0, 4, v0
	v_lshl_add_u32 v0, v253, 6, v0
	v_lshl_add_u32 v98, v235, 3, v234
	v_lshl_add_u32 v176, v98, 7, v0
	s_lshl_b32 s33, s80, 7
	v_lshl_add_u32 v177, v232, 7, v0
	v_subrev_u32_e32 v177, s33, v177
	v_lshlrev_b32_e32 v98, 7, v253
	v_sub_u32_e32 v178, 64, v98
	v_lshrrev_b32_e32 v98, 3, v184
	v_and_b32_e32 v99, 7, v184
	s_lshr_b32 s0, s80, 3
	s_and_b32 s1, s0, 1
	s_lshl_b32 s1, s1, 2
	v_and_b32_e32 v253, 3, v98
	v_or_b32_e32 v253, s1, v253
	v_xor_b32_e32 v253, v99, v253
	v_add_u32_e32 v0, s80, v98
	v_lshlrev_b32_e32 v174, 7, v0
	v_lshl_add_u32 v174, v253, 4, v174
	v_xor_b32_e32 v253, v99, v98
	v_lshlrev_b32_e32 v175, 10, v0
	v_lshl_add_u32 v175, v253, 4, v175
	s_add_i32 s94, s33, 0xa040
	s_add_i32 s95, s33, 0x1dc40
	s_add_i32 s46, s33, 0x20200
	s_lshr_b32 s15, s97, 13
	s_lshl_b32 s15, s15, 2
	s_and_b32 s1, s88, 3
	s_or_b32 s15, s15, s1
	s_lshl_b32 s15, s15, 16
	s_add_u32 s68, s30, 0x38110000
	s_addc_u32 s69, s31, 0
	s_add_u32 s68, s68, s15
	s_addc_u32 s69, s69, 0
	s_add_u32 s70, s30, 0x38210000
	s_addc_u32 s71, s31, 0
	s_add_u32 s70, s70, s15
	s_addc_u32 s71, s71, 0
	s_lshl_b32 s74, s34, 2
	s_add_i32 s74, s74, 66
	s_lshr_b32 s74, s74, 6
	s_mov_b32 s92, 0
	s_mov_b32 s93, 0
	s_lshl_b32 s0, s92, 13
	s_add_i32 s0, s0, s33
	s_add_i32 m0, s0, 16448
	s_lshl_b32 s1, s93, 13
	s_add_u32 s72, s68, s1
	s_addc_u32 s73, s69, 0
	global_load_lds_dwordx4 v174, s[72:73]
	s_cmp_eq_u32 s92, 1
	s_cselect_b32 s0, s95, s94
	s_cmp_eq_u32 s92, 2
	s_cselect_b32 m0, s46, s0
	s_lshl_b32 s1, s93, 7
	s_add_u32 s72, s70, s1
	s_addc_u32 s73, s71, 0
	global_load_lds_dwordx4 v175, s[72:73]
	s_add_i32 s93, s93, 1
	s_cmp_ge_i32 s93, s74
	s_cselect_b32 s93, 0, s93
	s_add_i32 s92, s92, 1
	s_cmp_eq_u32 s92, 3
	s_cselect_b32 s92, 0, s92
	s_lshl_b32 s0, s92, 13
	s_add_i32 s0, s0, s33
	s_add_i32 m0, s0, 16448
	s_lshl_b32 s1, s93, 13
	s_add_u32 s72, s68, s1
	s_addc_u32 s73, s69, 0
	global_load_lds_dwordx4 v174, s[72:73]
	s_cmp_eq_u32 s92, 1
	s_cselect_b32 s0, s95, s94
	s_cmp_eq_u32 s92, 2
	s_cselect_b32 m0, s46, s0
	s_lshl_b32 s1, s93, 7
	s_add_u32 s72, s70, s1
	s_addc_u32 s73, s71, 0
	global_load_lds_dwordx4 v175, s[72:73]
	s_add_i32 s93, s93, 1
	s_cmp_ge_i32 s93, s74
	s_cselect_b32 s93, 0, s93
	s_add_i32 s92, s92, 1
	s_cmp_eq_u32 s92, 3
	s_cselect_b32 s92, 0, s92
	s_lshl_b32 s0, s34, 6
	s_add_i32 s0, s0, s97
	s_add_i32 s0, s0, s80
	v_add_u32_e32 v253, s0, v234
	s_and_b32 s1, s88, 3
	s_lshl_b32 s1, s1, 2
	v_add_u32_e32 v98, s1, v235
	v_lshlrev_b32_e32 v98, 7, v98
	v_lshl_add_u32 v98, v253, 11, v98
	v_lshl_add_u32 v98, v233, 4, v98
	v_add_u32_e32 v99, 0x2000, v98
	s_add_u32 s72, s30, 0x29900000
	s_addc_u32 s73, s31, 0
	global_load_dwordx4 v[34:37], v98, s[72:73] offset:0
	global_load_dwordx4 v[38:41], v98, s[72:73] offset:64
	global_load_dwordx4 v[42:45], v99, s[72:73] offset:0
	global_load_dwordx4 v[46:49], v99, s[72:73] offset:64
; __device__ __forceinline__ bf16_t tobf(float x) { return (bf16_t)pk2(x, 0.f); }
; __device__ __forceinline__ float red16(float v) { v += __shfl_xor(v, 1); v += __shfl_xor(v, 2); v += __shfl_xor(v, 4); v += __shfl_xor(v, 8); return v; }
; template <int MODE> ...
;     ...
; #pragma unroll
;     for (int tile = 0; tile < 2; ++tile) { const int t0 = qb * 64 + wave * 8 + tile * 4;
; #pragma unroll
;         for (int tt = 0; tt < 4; ++tt) { const float gs = GN[(size_t)(b * SEQ + t0 + tt) * 48 + (g * 4 + q4) * 3 + (MODE ? 2 : 1)] / red16(ls[tile][tt]);
;             bf16_t* op = ONSA + (size_t)(b * SEQ + t0 + tt) * 1024 + (g * 4 + q4) * 64 + r16;
; #pragma unroll
;             for (int nt = 0; nt < 4; ++nt) op[nt * 16] = tobf(bflo((unsigned)op[nt * 16]) + gs * os[tile][nt][tt]); } }
; __device__ __forceinline__ void nsa_phase(LAS unsigned char* lds, const bf16_t* Q, const bf16_t* KV, const bf16_t* KCMP, const bf16_t* VCMPT, const float* GN, const float* rel_bias, bf16_t* ONSA,
;                                           int tid, int lane, int wave) {
;     ...
;                 nsa_block_loop<0>(bg, qb, Q, KV, GN, ONSA, btab, Pb, selall, masks, stage, tid, lane, wave);
;                 nsa_block_loop<1>(bg, qb, Q, KV, GN, ONSA, btab, Pb, selall, masks, stage, tid, lane, wave);
.Lepi_nopref:
	v_and_b32_e32 v66, 15, v184
	v_lshrrev_b32_e32 v67, 4, v184
	v_and_b32_e32 v68, 3, v66
	v_lshrrev_b32_e32 v69, 2, v66
	s_lshl_b32 s0, s18, 6
	s_add_i32 s0, s0, s97
	s_add_i32 s0, s0, s80
	v_add_u32_e32 v70, s0, v68
	s_and_b32 s1, s88, 3
	s_lshl_b32 s1, s1, 2
	v_add_u32_e32 v71, s1, v69
	v_lshlrev_b32_e32 v72, 7, v71
	v_lshl_add_u32 v72, v70, 11, v72
	v_lshl_add_u32 v72, v67, 3, v72
	v_add_u32_e32 v73, 0x2000, v72
	v_mul_u32_u24_e32 v74, 0xc0, v70
	v_mul_u32_u24_e32 v75, 12, v71
	s_lshl_b32 s0, s54, 2
	s_add_i32 s0, s0, 4
	v_add3_u32 v74, v74, v75, s0
	s_add_u32 s70, s30, 0x38310000
	s_addc_u32 s71, s31, 0
	s_add_u32 s14, s30, 0xf900000
	s_addc_u32 s15, s31, 0
	global_load_dword v76, v74, s[70:71] offset:0
	global_load_dword v77, v74, s[70:71] offset:768
	global_load_dwordx2 v[50:51], v72, s[14:15] offset:0
	global_load_dwordx2 v[52:53], v72, s[14:15] offset:32
	global_load_dwordx2 v[54:55], v72, s[14:15] offset:64
	global_load_dwordx2 v[56:57], v72, s[14:15] offset:96
	global_load_dwordx2 v[58:59], v73, s[14:15] offset:0
	global_load_dwordx2 v[60:61], v73, s[14:15] offset:32
	global_load_dwordx2 v[62:63], v73, s[14:15] offset:64
	global_load_dwordx2 v[64:65], v73, s[14:15] offset:96
	v_xor_b32_e32 v78, 16, v184
	v_lshlrev_b32_e32 v78, 2, v78
	v_xor_b32_e32 v79, 32, v184
	v_lshlrev_b32_e32 v79, 2, v79
	ds_bpermute_b32 v237, v78, v215
	s_waitcnt lgkmcnt(0)
	v_add_f32_e32 v236, v215, v237
	ds_bpermute_b32 v237, v79, v236
	s_waitcnt lgkmcnt(0)
	v_add_f32_e32 v236, v236, v237
	ds_bpermute_b32 v245, v78, v224
	s_waitcnt lgkmcnt(0)
	v_add_f32_e32 v244, v224, v245
	ds_bpermute_b32 v245, v79, v244
	s_waitcnt lgkmcnt(0)
	v_add_f32_e32 v244, v244, v245
	s_waitcnt vmcnt(9)
	v_div_scale_f32 v237, s[20:21], v236, v236, v76
	v_rcp_f32_e32 v238, v237
	v_div_scale_f32 v239, vcc, v76, v236, v76
	v_fma_f32 v240, -v237, v238, 1.0
	v_fmac_f32_e32 v238, v240, v238
	v_mul_f32_e32 v240, v239, v238
	v_fma_f32 v241, -v237, v240, v239
	v_fmac_f32_e32 v240, v241, v238
	v_fma_f32 v237, -v237, v240, v239
	s_nop 1
	v_div_fmas_f32 v237, v237, v238, v240
	v_div_fixup_f32 v239, v237, v236, v76
	s_waitcnt vmcnt(8)
	v_div_scale_f32 v245, s[20:21], v244, v244, v77
	v_rcp_f32_e32 v246, v245
	v_div_scale_f32 v247, vcc, v77, v244, v77
	v_fma_f32 v248, -v245, v246, 1.0
	v_fmac_f32_e32 v246, v248, v246
	v_mul_f32_e32 v248, v247, v246
	v_fma_f32 v249, -v245, v248, v247
	v_fmac_f32_e32 v248, v249, v246
	v_fma_f32 v245, -v245, v248, v247
	s_nop 1
	v_div_fmas_f32 v245, v245, v246, v248
	v_div_fixup_f32 v247, v245, v244, v77
	s_waitcnt vmcnt(7)
	v_lshlrev_b32_e32 v242, 16, v50
	v_and_b32_e32 v243, 0xffff0000, v50
	v_fmac_f32_e32 v242, v239, v2
	v_fmac_f32_e32 v243, v239, v3
	v_cvt_pk_bf16_f32 v82, v242, v243
	v_lshlrev_b32_e32 v242, 16, v51
	v_and_b32_e32 v243, 0xffff0000, v51
	v_fmac_f32_e32 v242, v239, v4
	v_fmac_f32_e32 v243, v239, v5
	v_cvt_pk_bf16_f32 v83, v242, v243
	s_waitcnt vmcnt(6)
	v_lshlrev_b32_e32 v242, 16, v52
	v_and_b32_e32 v243, 0xffff0000, v52
	v_fmac_f32_e32 v242, v239, v6
	v_fmac_f32_e32 v243, v239, v7
	v_cvt_pk_bf16_f32 v84, v242, v243
	v_lshlrev_b32_e32 v242, 16, v53
	v_and_b32_e32 v243, 0xffff0000, v53
	v_fmac_f32_e32 v242, v239, v8
	v_fmac_f32_e32 v243, v239, v9
	v_cvt_pk_bf16_f32 v85, v242, v243
	s_waitcnt vmcnt(5)
	v_lshlrev_b32_e32 v242, 16, v54
	v_and_b32_e32 v243, 0xffff0000, v54
	v_fmac_f32_e32 v242, v239, v10
	v_fmac_f32_e32 v243, v239, v11
	v_cvt_pk_bf16_f32 v86, v242, v243
	v_lshlrev_b32_e32 v242, 16, v55
	v_and_b32_e32 v243, 0xffff0000, v55
	v_fmac_f32_e32 v242, v239, v12
	v_fmac_f32_e32 v243, v239, v13
	v_cvt_pk_bf16_f32 v87, v242, v243
	s_waitcnt vmcnt(4)
	v_lshlrev_b32_e32 v242, 16, v56
	v_and_b32_e32 v243, 0xffff0000, v56
	v_fmac_f32_e32 v242, v239, v14
	v_fmac_f32_e32 v243, v239, v15
	v_cvt_pk_bf16_f32 v88, v242, v243
	v_lshlrev_b32_e32 v242, 16, v57
	v_and_b32_e32 v243, 0xffff0000, v57
	v_fmac_f32_e32 v242, v239, v16
	v_fmac_f32_e32 v243, v239, v17
	v_cvt_pk_bf16_f32 v89, v242, v243
	s_waitcnt vmcnt(3)
	v_lshlrev_b32_e32 v250, 16, v58
	v_and_b32_e32 v251, 0xffff0000, v58
	v_fmac_f32_e32 v250, v247, v18
	v_fmac_f32_e32 v251, v247, v19
	v_cvt_pk_bf16_f32 v90, v250, v251
	v_lshlrev_b32_e32 v250, 16, v59
	v_and_b32_e32 v251, 0xffff0000, v59
	v_fmac_f32_e32 v250, v247, v20
	v_fmac_f32_e32 v251, v247, v21
	v_cvt_pk_bf16_f32 v91, v250, v251
	s_waitcnt vmcnt(2)
	v_lshlrev_b32_e32 v250, 16, v60
	v_and_b32_e32 v251, 0xffff0000, v60
	v_fmac_f32_e32 v250, v247, v22
	v_fmac_f32_e32 v251, v247, v23
	v_cvt_pk_bf16_f32 v92, v250, v251
	v_lshlrev_b32_e32 v250, 16, v61
	v_and_b32_e32 v251, 0xffff0000, v61
	v_fmac_f32_e32 v250, v247, v24
	v_fmac_f32_e32 v251, v247, v25
	v_cvt_pk_bf16_f32 v93, v250, v251
	s_waitcnt vmcnt(1)
	v_lshlrev_b32_e32 v250, 16, v62
	v_and_b32_e32 v251, 0xffff0000, v62
	v_fmac_f32_e32 v250, v247, v26
	v_fmac_f32_e32 v251, v247, v27
	v_cvt_pk_bf16_f32 v94, v250, v251
	v_lshlrev_b32_e32 v250, 16, v63
	v_and_b32_e32 v251, 0xffff0000, v63
	v_fmac_f32_e32 v250, v247, v28
	v_fmac_f32_e32 v251, v247, v29
	v_cvt_pk_bf16_f32 v95, v250, v251
	s_waitcnt vmcnt(0)
	v_lshlrev_b32_e32 v250, 16, v64
	v_and_b32_e32 v251, 0xffff0000, v64
	v_fmac_f32_e32 v250, v247, v30
	v_fmac_f32_e32 v251, v247, v31
	v_cvt_pk_bf16_f32 v96, v250, v251
	v_lshlrev_b32_e32 v250, 16, v65
	v_and_b32_e32 v251, 0xffff0000, v65
	v_fmac_f32_e32 v250, v247, v32
	v_fmac_f32_e32 v251, v247, v33
	v_cvt_pk_bf16_f32 v97, v250, v251
	global_store_dwordx2 v72, v[82:83], s[14:15] offset:0
	global_store_dwordx2 v72, v[84:85], s[14:15] offset:32
	global_store_dwordx2 v72, v[86:87], s[14:15] offset:64
	global_store_dwordx2 v72, v[88:89], s[14:15] offset:96
	global_store_dwordx2 v73, v[90:91], s[14:15] offset:0
	global_store_dwordx2 v73, v[92:93], s[14:15] offset:32
	global_store_dwordx2 v73, v[94:95], s[14:15] offset:64
	global_store_dwordx2 v73, v[96:97], s[14:15] offset:96
	s_waitcnt vmcnt(0)
	s_add_i32 s54, s54, 1
	s_cmp_eq_u32 s54, 1
	s_cbranch_scc1 .Lnsa_mode_top
	v_cmp_gt_u32_e32 vcc, 0x44, v183
	s_nop 0
	s_and_saveexec_b64 s[20:21], vcc
	s_cbranch_execz .Lnsa_zskip_30
	v_lshlrev_b32_e32 v50, 2, v183
	v_add_u32_e32 v50, 0x1fc40, v50
	ds_write_b32 v50, v1
